# input-projection GEMM: tail N-tiles (16 / 48 valid columns) run a K-loop copy that skips the MFMA half-runs whose output columns are all beyond nvalid
# speedup vs baseline: 1.0065x; 1.0065x over previous
.Lip_tail_loop:
	s_add_u32 s8, s4, 0xfffc0080
	s_addc_u32 s9, s5, -1
	s_add_i32 s38, 0, 0x10000
	s_cmp_eq_u32 s35, 12
	s_cselect_b32 s25, s1, s9
	s_cselect_b32 s24, s26, s8
	v_add_u32_e32 v0, s38, v189
	s_cselect_b32 s9, s27, s34
	s_cselect_b32 s8, s28, s29
	s_add_i32 s64, 0, 0x14000
	s_waitcnt lgkmcnt(0)
	ds_read_b128 v[142:145], v0
	ds_read_b128 v[146:149], v0 offset:1024
	ds_read_b128 v[150:153], v0 offset:2048
	ds_read_b128 v[154:157], v0 offset:3072
	v_add_u32_e32 v0, s64, v189
	ds_read_b128 v[170:173], v0
	ds_read_b128 v[174:177], v0 offset:1024
	ds_read_b128 v[178:181], v0 offset:2048
	ds_read_b128 v[182:185], v0 offset:3072
	v_lshl_add_u64 v[186:187], s[4:5], 0, v[140:141]
	s_add_i32 m0, s67, 0xc000
	ds_read_b128 v[194:197], v193
	ds_read_b128 v[198:201], v193 offset:1024
	ds_read_b128 v[206:209], v193 offset:2048
	ds_read_b128 v[210:213], v193 offset:3072
	ds_read_b128 v[214:217], v193 offset:4096
	ds_read_b128 v[238:241], v193 offset:5120
	ds_read_b128 v[242:245], v193 offset:6144
	ds_read_b128 v[246:249], v193 offset:7168
	global_load_lds_dwordx4 v[186:187], off
	v_lshl_add_u64 v[186:187], s[4:5], 0, v[138:139]
	s_add_i32 m0, s67, 0xe000
	s_nop 0
	global_load_lds_dwordx4 v[186:187], off
	s_waitcnt vmcnt(8)
	s_waitcnt lgkmcnt(0)
	s_barrier
	s_waitcnt lgkmcnt(0)
	s_bitcmp1_b32 s101, 0
	s_cbranch_scc1 .Lip_skipA0
	v_mfma_f32_16x16x32_bf16 v[126:129], v[142:145], v[194:197], v[126:129]
	v_mfma_f32_16x16x32_bf16 v[122:125], v[150:153], v[194:197], v[122:125]
	v_mfma_f32_16x16x32_bf16 v[110:113], v[142:145], v[206:209], v[110:113]
	v_mfma_f32_16x16x32_bf16 v[106:109], v[150:153], v[206:209], v[106:109]
	v_mfma_f32_16x16x32_bf16 v[94:97], v[142:145], v[214:217], v[94:97]
	v_mfma_f32_16x16x32_bf16 v[90:93], v[150:153], v[214:217], v[90:93]
	v_mfma_f32_16x16x32_bf16 v[78:81], v[142:145], v[242:245], v[78:81]
	v_mfma_f32_16x16x32_bf16 v[74:77], v[150:153], v[242:245], v[74:77]
	v_mfma_f32_16x16x32_bf16 v[126:129], v[146:149], v[198:201], v[126:129]
	v_mfma_f32_16x16x32_bf16 v[122:125], v[154:157], v[198:201], v[122:125]
	v_mfma_f32_16x16x32_bf16 v[110:113], v[146:149], v[210:213], v[110:113]
	v_mfma_f32_16x16x32_bf16 v[106:109], v[154:157], v[210:213], v[106:109]
	v_mfma_f32_16x16x32_bf16 v[94:97], v[146:149], v[238:241], v[94:97]
	v_mfma_f32_16x16x32_bf16 v[90:93], v[154:157], v[238:241], v[90:93]
	v_mfma_f32_16x16x32_bf16 v[78:81], v[146:149], v[246:249], v[78:81]
	v_mfma_f32_16x16x32_bf16 v[74:77], v[154:157], v[246:249], v[74:77]
.Lip_skipA0:
	s_bitcmp1_b32 s101, 1
	s_cbranch_scc1 .Lip_skipB0
	v_mfma_f32_16x16x32_bf16 v[118:121], v[170:173], v[194:197], v[118:121]
	v_mfma_f32_16x16x32_bf16 v[114:117], v[178:181], v[194:197], v[114:117]
	v_mfma_f32_16x16x32_bf16 v[102:105], v[170:173], v[206:209], v[102:105]
	v_mfma_f32_16x16x32_bf16 v[98:101], v[178:181], v[206:209], v[98:101]
	v_mfma_f32_16x16x32_bf16 v[86:89], v[170:173], v[214:217], v[86:89]
	v_mfma_f32_16x16x32_bf16 v[82:85], v[178:181], v[214:217], v[82:85]
	v_mfma_f32_16x16x32_bf16 v[70:73], v[170:173], v[242:245], v[70:73]
	v_mfma_f32_16x16x32_bf16 v[66:69], v[178:181], v[242:245], v[66:69]
	v_mfma_f32_16x16x32_bf16 v[118:121], v[174:177], v[198:201], v[118:121]
	v_mfma_f32_16x16x32_bf16 v[114:117], v[182:185], v[198:201], v[114:117]
	v_mfma_f32_16x16x32_bf16 v[102:105], v[174:177], v[210:213], v[102:105]
	v_mfma_f32_16x16x32_bf16 v[98:101], v[182:185], v[210:213], v[98:101]
	v_mfma_f32_16x16x32_bf16 v[86:89], v[174:177], v[238:241], v[86:89]
	v_mfma_f32_16x16x32_bf16 v[82:85], v[182:185], v[238:241], v[82:85]
	v_mfma_f32_16x16x32_bf16 v[70:73], v[174:177], v[246:249], v[70:73]
	v_mfma_f32_16x16x32_bf16 v[66:69], v[182:185], v[246:249], v[66:69]
.Lip_skipB0:
	s_barrier
	s_add_i32 s38, s38, s66
	v_lshl_add_u64 v[186:187], s[8:9], 0, v[132:133]
	s_mov_b32 m0, s38
	ds_read_b128 v[194:197], v193 offset:16384
	ds_read_b128 v[198:201], v193 offset:17408
	ds_read_b128 v[206:209], v193 offset:18432
	ds_read_b128 v[210:213], v193 offset:19456
	ds_read_b128 v[214:217], v193 offset:20480
	ds_read_b128 v[238:241], v193 offset:21504
	ds_read_b128 v[242:245], v193 offset:22528
	ds_read_b128 v[246:249], v193 offset:23552
	global_load_lds_dwordx4 v[186:187], off
	s_add_i32 m0, s38, 0x2000
	s_add_u32 s38, s8, 0x40000
	v_lshl_add_u64 v[202:203], s[8:9], 0, v[136:137]
	s_addc_u32 s39, s9, 0
	s_add_i32 s64, s64, s66
	global_load_lds_dwordx4 v[202:203], off
	v_lshl_add_u64 v[220:221], s[38:39], 0, v[132:133]
	s_mov_b32 m0, s64
	v_lshl_add_u64 v[250:251], s[24:25], 0, v[134:135]
	global_load_lds_dwordx4 v[220:221], off
	v_lshl_add_u64 v[220:221], s[38:39], 0, v[136:137]
	s_add_i32 m0, s64, 0x2000
	s_nop 0
	global_load_lds_dwordx4 v[220:221], off
	v_lshl_add_u64 v[220:221], s[24:25], 0, v[130:131]
	s_mov_b32 m0, s67
	s_nop 0
	global_load_lds_dwordx4 v[220:221], off
	s_mov_b32 m0, s73
	s_nop 0
	global_load_lds_dwordx4 v[250:251], off
	s_waitcnt vmcnt(8)
	s_waitcnt lgkmcnt(0)
	s_barrier
	s_waitcnt lgkmcnt(0)
	s_bitcmp1_b32 s101, 0
	s_cbranch_scc1 .Lip_skipA1
	v_mfma_f32_16x16x32_bf16 v[62:65], v[142:145], v[194:197], v[62:65]
	v_mfma_f32_16x16x32_bf16 v[58:61], v[150:153], v[194:197], v[58:61]
	v_mfma_f32_16x16x32_bf16 v[46:49], v[142:145], v[206:209], v[46:49]
	v_mfma_f32_16x16x32_bf16 v[42:45], v[150:153], v[206:209], v[42:45]
	v_mfma_f32_16x16x32_bf16 v[30:33], v[142:145], v[214:217], v[30:33]
	v_mfma_f32_16x16x32_bf16 v[26:29], v[150:153], v[214:217], v[26:29]
	v_mfma_f32_16x16x32_bf16 v[14:17], v[142:145], v[242:245], v[14:17]
	v_mfma_f32_16x16x32_bf16 v[10:13], v[150:153], v[242:245], v[10:13]
	v_mfma_f32_16x16x32_bf16 v[62:65], v[146:149], v[198:201], v[62:65]
	v_mfma_f32_16x16x32_bf16 v[58:61], v[154:157], v[198:201], v[58:61]
	v_mfma_f32_16x16x32_bf16 v[46:49], v[146:149], v[210:213], v[46:49]
	v_mfma_f32_16x16x32_bf16 v[42:45], v[154:157], v[210:213], v[42:45]
	v_mfma_f32_16x16x32_bf16 v[30:33], v[146:149], v[238:241], v[30:33]
	v_mfma_f32_16x16x32_bf16 v[26:29], v[154:157], v[238:241], v[26:29]
	v_mfma_f32_16x16x32_bf16 v[14:17], v[146:149], v[246:249], v[14:17]
	v_mfma_f32_16x16x32_bf16 v[10:13], v[154:157], v[246:249], v[10:13]
.Lip_skipA1:
	s_bitcmp1_b32 s101, 1
	s_cbranch_scc1 .Lip_skipB1
	v_mfma_f32_16x16x32_bf16 v[54:57], v[170:173], v[194:197], v[54:57]
	v_mfma_f32_16x16x32_bf16 v[50:53], v[178:181], v[194:197], v[50:53]
	v_mfma_f32_16x16x32_bf16 v[38:41], v[170:173], v[206:209], v[38:41]
	v_mfma_f32_16x16x32_bf16 v[34:37], v[178:181], v[206:209], v[34:37]
	v_mfma_f32_16x16x32_bf16 v[22:25], v[170:173], v[214:217], v[22:25]
	v_mfma_f32_16x16x32_bf16 v[18:21], v[178:181], v[214:217], v[18:21]
	v_mfma_f32_16x16x32_bf16 v[6:9], v[170:173], v[242:245], v[6:9]
	v_mfma_f32_16x16x32_bf16 v[2:5], v[178:181], v[242:245], v[2:5]
	v_mfma_f32_16x16x32_bf16 v[54:57], v[174:177], v[198:201], v[54:57]
	v_mfma_f32_16x16x32_bf16 v[50:53], v[182:185], v[198:201], v[50:53]
	v_mfma_f32_16x16x32_bf16 v[38:41], v[174:177], v[210:213], v[38:41]
	v_mfma_f32_16x16x32_bf16 v[34:37], v[182:185], v[210:213], v[34:37]
	v_mfma_f32_16x16x32_bf16 v[22:25], v[174:177], v[238:241], v[22:25]
	v_mfma_f32_16x16x32_bf16 v[18:21], v[182:185], v[238:241], v[18:21]
	v_mfma_f32_16x16x32_bf16 v[6:9], v[174:177], v[246:249], v[6:9]
	v_mfma_f32_16x16x32_bf16 v[2:5], v[182:185], v[246:249], v[2:5]
.Lip_skipB1:
	s_barrier
	s_add_i32 s38, 0, 0x18000
	v_add_u32_e32 v0, s38, v189
	s_add_i32 s39, 0, 0x1c000
	ds_read_b128 v[142:145], v0
	ds_read_b128 v[146:149], v0 offset:1024
	ds_read_b128 v[150:153], v0 offset:2048
	ds_read_b128 v[154:157], v0 offset:3072
	v_add_u32_e32 v0, s39, v189
	ds_read_b128 v[170:173], v0
	ds_read_b128 v[174:177], v0 offset:1024
	ds_read_b128 v[178:181], v0 offset:2048
	ds_read_b128 v[182:185], v0 offset:3072
	s_add_u32 s24, s24, 0x40000
	s_addc_u32 s25, s25, 0
	s_mov_b32 m0, s20
	v_lshl_add_u64 v[226:227], s[24:25], 0, v[130:131]
	ds_read_b128 v[194:197], v193 offset:32768
	ds_read_b128 v[198:201], v193 offset:33792
	ds_read_b128 v[206:209], v193 offset:34816
	ds_read_b128 v[210:213], v193 offset:35840
	ds_read_b128 v[214:217], v193 offset:36864
	ds_read_b128 v[238:241], v193 offset:37888
	ds_read_b128 v[242:245], v193 offset:38912
	ds_read_b128 v[246:249], v193 offset:39936
	global_load_lds_dwordx4 v[226:227], off
	v_lshl_add_u64 v[226:227], s[24:25], 0, v[134:135]
	s_mov_b32 m0, s21
	s_nop 0
	global_load_lds_dwordx4 v[226:227], off
	s_waitcnt vmcnt(8)
	s_waitcnt lgkmcnt(0)
	s_barrier
	s_waitcnt lgkmcnt(0)
	s_bitcmp1_b32 s101, 0
	s_cbranch_scc1 .Lip_skipA2
	v_mfma_f32_16x16x32_bf16 v[126:129], v[142:145], v[194:197], v[126:129]
	v_mfma_f32_16x16x32_bf16 v[122:125], v[150:153], v[194:197], v[122:125]
	v_mfma_f32_16x16x32_bf16 v[110:113], v[142:145], v[206:209], v[110:113]
	v_mfma_f32_16x16x32_bf16 v[106:109], v[150:153], v[206:209], v[106:109]
	v_mfma_f32_16x16x32_bf16 v[94:97], v[142:145], v[214:217], v[94:97]
	v_mfma_f32_16x16x32_bf16 v[90:93], v[150:153], v[214:217], v[90:93]
	v_mfma_f32_16x16x32_bf16 v[78:81], v[142:145], v[242:245], v[78:81]
	v_mfma_f32_16x16x32_bf16 v[74:77], v[150:153], v[242:245], v[74:77]
	v_mfma_f32_16x16x32_bf16 v[126:129], v[146:149], v[198:201], v[126:129]
	v_mfma_f32_16x16x32_bf16 v[122:125], v[154:157], v[198:201], v[122:125]
	v_mfma_f32_16x16x32_bf16 v[110:113], v[146:149], v[210:213], v[110:113]
	v_mfma_f32_16x16x32_bf16 v[106:109], v[154:157], v[210:213], v[106:109]
	v_mfma_f32_16x16x32_bf16 v[94:97], v[146:149], v[238:241], v[94:97]
	v_mfma_f32_16x16x32_bf16 v[90:93], v[154:157], v[238:241], v[90:93]
	v_mfma_f32_16x16x32_bf16 v[78:81], v[146:149], v[246:249], v[78:81]
	v_mfma_f32_16x16x32_bf16 v[74:77], v[154:157], v[246:249], v[74:77]

.Lip_skipB2:
	s_barrier
	s_add_i32 s24, s38, s66
	v_lshl_add_u64 v[186:187], v[186:187], 0, s[22:23]
	s_mov_b32 m0, s24
	ds_read_b128 v[194:197], v193 offset:49152
	ds_read_b128 v[198:201], v193 offset:50176
	ds_read_b128 v[206:209], v193 offset:51200
	ds_read_b128 v[210:213], v193 offset:52224
	ds_read_b128 v[214:217], v193 offset:53248
	ds_read_b128 v[238:241], v193 offset:54272
	ds_read_b128 v[242:245], v193 offset:55296
	ds_read_b128 v[246:249], v193 offset:56320
	global_load_lds_dwordx4 v[186:187], off
	s_add_i32 m0, s24, 0x2000
	s_add_u32 s8, s8, 0x40080
	v_lshl_add_u64 v[186:187], v[202:203], 0, s[22:23]
	s_addc_u32 s9, s9, 0
	s_add_i32 s24, s39, s66
	global_load_lds_dwordx4 v[186:187], off
	v_lshl_add_u64 v[186:187], s[8:9], 0, v[132:133]
	s_mov_b32 m0, s24
	s_nop 0
	global_load_lds_dwordx4 v[186:187], off
	v_lshl_add_u64 v[186:187], s[8:9], 0, v[136:137]
	s_add_i32 m0, s24, 0x2000
	s_nop 0
	global_load_lds_dwordx4 v[186:187], off
	v_lshl_add_u64 v[186:187], v[220:221], 0, s[22:23]
	s_mov_b32 m0, s6
	s_nop 0
	global_load_lds_dwordx4 v[186:187], off
	v_lshl_add_u64 v[186:187], v[250:251], 0, s[22:23]
	s_mov_b32 m0, s7
	s_nop 0
	global_load_lds_dwordx4 v[186:187], off
	s_waitcnt vmcnt(8)
	s_waitcnt lgkmcnt(0)
	s_barrier
	s_waitcnt lgkmcnt(0)
	s_bitcmp1_b32 s101, 0
	s_cbranch_scc1 .Lip_skipA3
	v_mfma_f32_16x16x32_bf16 v[62:65], v[142:145], v[194:197], v[62:65]
	v_mfma_f32_16x16x32_bf16 v[58:61], v[150:153], v[194:197], v[58:61]
	v_mfma_f32_16x16x32_bf16 v[46:49], v[142:145], v[206:209], v[46:49]
	v_mfma_f32_16x16x32_bf16 v[42:45], v[150:153], v[206:209], v[42:45]
	v_mfma_f32_16x16x32_bf16 v[30:33], v[142:145], v[214:217], v[30:33]
	v_mfma_f32_16x16x32_bf16 v[26:29], v[150:153], v[214:217], v[26:29]
	v_mfma_f32_16x16x32_bf16 v[14:17], v[142:145], v[242:245], v[14:17]
	v_mfma_f32_16x16x32_bf16 v[10:13], v[150:153], v[242:245], v[10:13]
	v_mfma_f32_16x16x32_bf16 v[62:65], v[146:149], v[198:201], v[62:65]
	v_mfma_f32_16x16x32_bf16 v[58:61], v[154:157], v[198:201], v[58:61]
	v_mfma_f32_16x16x32_bf16 v[46:49], v[146:149], v[210:213], v[46:49]
	v_mfma_f32_16x16x32_bf16 v[42:45], v[154:157], v[210:213], v[42:45]
	v_mfma_f32_16x16x32_bf16 v[30:33], v[146:149], v[238:241], v[30:33]
	v_mfma_f32_16x16x32_bf16 v[26:29], v[154:157], v[238:241], v[26:29]
	v_mfma_f32_16x16x32_bf16 v[14:17], v[146:149], v[246:249], v[14:17]
	v_mfma_f32_16x16x32_bf16 v[10:13], v[154:157], v[246:249], v[10:13]

.Lip_skipB3:
	s_barrier
	s_add_i32 s35, s35, 2
	s_add_u32 s29, s29, 0x100
	s_addc_u32 s34, s34, 0
	s_add_u32 s4, s4, 0x100
	s_addc_u32 s5, s5, 0
	s_cmp_gt_u32 s35, 13
	s_cbranch_scc0 .Lip_tail_loop
	s_branch .Lip_loop_exit

.Lprio_skip_ip:
	v_readfirstlane_b32 vcc_lo, v169
	s_lshl_b32 s101, s72, 8
	s_sub_i32 s101, s31, s101
	s_lshr_b32 vcc_lo, vcc_lo, 1
	s_and_b32 vcc_lo, vcc_lo, 0x60
	s_cmp_ge_i32 vcc_lo, s101
	s_cselect_b32 vcc_lo, 1, 0
	s_cmp_le_i32 s101, 0x80
	s_cselect_b32 s101, 2, 0
	s_or_b32 s101, s101, vcc_lo
	s_cmp_lg_u32 s101, 0
	s_cbranch_scc1 .Lip_tail_loop

.Lip_loop_exit:
	s_setprio 0
	v_readlane_b32 s4, v254, 44
	v_readlane_b32 s5, v254, 45
	s_and_b64 vcc, exec, s[4:5]
	s_cbranch_vccz .LBB0_595
	s_barrier
